# MLA fast loop: loop-invariant mask/copy VALU hoisted to exit and fallback stub, lrun accumulated in place; MFMA->VALU hazard padding made explicit (s_nop 8)
# baseline (speedup 1.0000x reference)
; #define LAS __attribute__((address_space(3)))
; template <int DQ>
; DI void attn_item(const Frame& F, const AttnItem& it, const LAS float* rpb_lds) {
;     ...
;     auto lstore = [&](int ti) {
;         LAS unsigned char* kb = base + (ti & 1) * KBYTES; LAS unsigned char* vb = base + 2 * KBYTES + (ti % 3) * VBYTES;
; #pragma unroll
;         for (int i = 0; i < 2; ++i) { const int id = tid + i * NT; *(LAS u32x4*)(kb + ((id >> 4) * KP + (id & 15) * 8) * 2) = rk[i];
;             *(LAS u32x4*)(vb + ((id >> 3) * VP + (id & 7) * 8) * 2) = rv[i]; }
;         if (DQ == 192) *(LAS u32x4*)(kb + ((tid >> 3) * KP + 128 + (tid & 7) * 8) * 2) = rr;
;     };
;     ...
;     auto qk = [&](int ti) {
;         if (!active(ti)) return;
;         const int krow_l = (qq & 3) + 4 * ((qq >> 3) & 1) + 8 * ((qq >> 2) & 1) + 16 * (qq >> 4);
;         LAS unsigned char* kb = base + (ti & 1) * KBYTES + (krow_l * KP + 8 * hh) * 2;
; #pragma unroll
;         for (int blk = 0; blk < 2; ++blk)
; #pragma unroll
;             for (int i = 0; i < 16; ++i) s[blk][i] = 0.f;
;         bf16x8 kf[3][2];
; #pragma unroll
;         for (int p = 0; p < 2; ++p)
; #pragma unroll
;             for (int blk = 0; blk < 2; ++blk) kf[p][blk] = *(const LAS bf16x8*)(kb + (32 * blk * KP + 16 * p) * 2);
; #pragma unroll
;         for (int ks = 0; ks < KS; ++ks) {
;             if (ks + 2 < KS) {
; #pragma unroll
;                 for (int blk = 0; blk < 2; ++blk) kf[(ks + 2) % 3][blk] = *(const LAS bf16x8*)(kb + (32 * blk * KP + 16 * (ks + 2)) * 2); }
;             __builtin_amdgcn_sched_barrier(0);
; #pragma unroll
;             for (int blk = 0; blk < 2; ++blk) s[blk] = __builtin_amdgcn_mfma_f32_32x32x16_bf16(kf[ks % 3][blk], qf[ks], s[blk], 0, 0, 0);
;             __builtin_amdgcn_sched_barrier(0);
;         }
;     };
.Lfast_1347:
	s_mul_hi_u32 s4, s17, 0xaaaaaaab
	s_lshr_b32 s4, s4, 1
	s_mul_i32 s4, s4, 0xd800
	s_and_b32 s12, 1, s18
	v_subrev_u32_e32 v180, s4, v213
	v_subrev_u32_e32 v181, s4, v214
	s_cselect_b32 s4, 0x6400, 0
	v_add_u32_e32 v182, s4, v212
	ds_read_b128 v[80:83], v182 offset:12800
	ds_read_b128 v[84:87], v182
	ds_read_b128 v[176:179], v182 offset:32
	ds_read_b128 v[218:221], v182 offset:12832
	ds_read_b128 v[222:225], v182 offset:64
	ds_read_b128 v[226:229], v182 offset:12864
	s_waitcnt lgkmcnt(4)
	v_mfma_f32_32x32x16_bf16 v[96:111], v[84:87], v[144:147], 0
	v_mfma_f32_32x32x16_bf16 v[80:95], v[80:83], v[144:147], 0
	ds_read_b128 v[230:233], v182 offset:96
	ds_read_b128 v[234:237], v182 offset:12896
	s_waitcnt lgkmcnt(4)
	v_mfma_f32_32x32x16_bf16 v[96:111], v[176:179], v[140:143], v[96:111]
	v_mfma_f32_32x32x16_bf16 v[80:95], v[218:221], v[140:143], v[80:95]
	ds_read_b128 v[176:179], v182 offset:128
	ds_read_b128 v[218:221], v182 offset:12928
	s_waitcnt lgkmcnt(4)
	v_mfma_f32_32x32x16_bf16 v[96:111], v[222:225], v[136:139], v[96:111]
	v_mfma_f32_32x32x16_bf16 v[80:95], v[226:229], v[136:139], v[80:95]
	ds_read_b128 v[222:225], v182 offset:160
	ds_read_b128 v[226:229], v182 offset:12960
	s_waitcnt lgkmcnt(4)
	v_mfma_f32_32x32x16_bf16 v[96:111], v[230:233], v[132:135], v[96:111]
	v_mfma_f32_32x32x16_bf16 v[80:95], v[234:237], v[132:135], v[80:95]
	ds_read_b128 v[230:233], v182 offset:192
	ds_read_b128 v[234:237], v182 offset:12992
	s_waitcnt lgkmcnt(4)
	v_mfma_f32_32x32x16_bf16 v[96:111], v[176:179], v[128:131], v[96:111]
	v_mfma_f32_32x32x16_bf16 v[80:95], v[218:221], v[128:131], v[80:95]
	ds_read_b128 v[176:179], v182 offset:224
	ds_read_b128 v[218:221], v182 offset:13024
	s_waitcnt lgkmcnt(4)
	v_mfma_f32_32x32x16_bf16 v[96:111], v[222:225], v[124:127], v[96:111]
	v_mfma_f32_32x32x16_bf16 v[80:95], v[226:229], v[124:127], v[80:95]
	ds_read_b128 v[222:225], v182 offset:256
	ds_read_b128 v[226:229], v182 offset:13056
	s_waitcnt lgkmcnt(4)
	v_mfma_f32_32x32x16_bf16 v[96:111], v[230:233], v[120:123], v[96:111]
	v_mfma_f32_32x32x16_bf16 v[80:95], v[234:237], v[120:123], v[80:95]
	ds_read_b128 v[230:233], v182 offset:288
	ds_read_b128 v[234:237], v182 offset:13088
	s_waitcnt lgkmcnt(4)
	v_mfma_f32_32x32x16_bf16 v[96:111], v[176:179], v[116:119], v[96:111]
	v_mfma_f32_32x32x16_bf16 v[80:95], v[218:221], v[116:119], v[80:95]
	ds_read_b128 v[176:179], v182 offset:320
	ds_read_b128 v[218:221], v182 offset:13120
	s_waitcnt lgkmcnt(4)
	v_mfma_f32_32x32x16_bf16 v[96:111], v[222:225], v[112:115], v[96:111]
	v_mfma_f32_32x32x16_bf16 v[80:95], v[226:229], v[112:115], v[80:95]
	ds_read_b128 v[222:225], v182 offset:352
	ds_read_b128 v[226:229], v182 offset:13152
	s_waitcnt lgkmcnt(0)
	v_mfma_f32_32x32x16_bf16 v[96:111], v[230:233], v[10:13], v[96:111]
	v_mfma_f32_32x32x16_bf16 v[80:95], v[234:237], v[10:13], v[80:95]
	v_mfma_f32_32x32x16_bf16 v[96:111], v[176:179], v[6:9], v[96:111]
	v_mfma_f32_32x32x16_bf16 v[80:95], v[218:221], v[6:9], v[80:95]
	v_mfma_f32_32x32x16_bf16 v[96:111], v[222:225], v[2:5], v[96:111]
	v_mfma_f32_32x32x16_bf16 v[80:95], v[226:229], v[2:5], v[80:95]
	s_andn2_b64 vcc, exec, s[8:9]
	s_cbranch_vccnz .Lfast_1353
	s_cmp_eq_u32 s12, 1
	s_cselect_b32 s6, 0, 0x6400
	s_add_i32 s6, s6, 0
	v_add_u32_e32 v176, s6, v209
	s_waitcnt vmcnt(0)
	ds_write_b128 v176, v[164:167]
	s_waitcnt vmcnt(3)
	ds_write_b128 v181, v[160:163]
	v_add_u32_e32 v160, s6, v210
	s_waitcnt vmcnt(2)
	ds_write_b128 v160, v[156:159]
	s_waitcnt vmcnt(1)
	ds_write_b128 v180, v[152:155]
	v_add_u32_e32 v152, s6, v211
	s_cmp_ge_u32 s18, s3
	s_mov_b64 s[6:7], -1
	s_waitcnt vmcnt(0)
	ds_write_b128 v152, v[148:151]
	s_cbranch_scc0 .Lfast_1350
	s_add_i32 s6, s15, s19
	s_add_i32 s13, s6, 0xfffff000
	s_mov_b64 s[6:7], 0

; #define LAS __attribute__((address_space(3)))
; DI unsigned pk2(float a, float b) { f32x2 v = {a, b}; bfv2 r = __builtin_convertvector(v, bfv2); return __builtin_bit_cast(unsigned, r); }
; DI float shx(float v, int m, int lane) { return __builtin_bit_cast(float, __builtin_amdgcn_ds_bpermute((lane ^ m) << 2, __builtin_bit_cast(int, v))); }
; template <int DQ>
; DI void attn_item(const Frame& F, const AttnItem& it, const LAS float* rpb_lds) {
;     ...
;         float mx = s[0][0];
; #pragma unroll
;         for (int blk = 0; blk < 2; ++blk)
; #pragma unroll
;             for (int i = 0; i < 16; ++i) mx = fmaxf(mx, s[blk][i]);
;         mx = fmaxf(mx, shx(mx, 32, lane));
;         const float mnew = fmaxf(mrun, mx), alpha = __builtin_amdgcn_exp2f(mrun - mnew);
;         mrun = mnew;
;         float ps = 0.f;
; #pragma unroll
;         for (int blk = 0; blk < 2; ++blk)
; #pragma unroll
;             for (int i = 0; i < 16; ++i) { const float p = __builtin_amdgcn_exp2f(s[blk][i] - mnew); s[blk][i] = p; ps += p; }
;         lrun = lrun * alpha + ps;
;         if (__builtin_amdgcn_ballot_w64(alpha != 1.f) != 0ull) {
; #pragma unroll
;             for (int db = 0; db < 4; ++db)
; #pragma unroll
;                 for (int i = 0; i < 16; ++i) o[db][i] *= alpha;
;         }
;         LAS unsigned char* vq = vb + (qq * VP + 8 * hh) * 2;
;         auto vload = [&](int step, int db) { return *(const LAS bf16x8*)(vq + (32 * db * VP + 16 * step) * 2); };
;         bf16x8 vf[2][4];
; #pragma unroll
;         for (int db = 0; db < 4; ++db) vf[0][db] = vload(0, db);
; #pragma unroll
;         for (int st = 0; st < 4; ++st) {
;             if (st + 1 < 4) {
; #pragma unroll
;                 for (int db = 0; db < 4; ++db) vf[(st + 1) & 1][db] = vload(st + 1, db); }
;             __builtin_amdgcn_sched_barrier(0);
;             const int blk = st >> 1, s2 = st & 1;
;             u32x4 pw; pw.x = pk2(s[blk][8 * s2], s[blk][8 * s2 + 1]); pw.y = pk2(s[blk][8 * s2 + 2], s[blk][8 * s2 + 3]);
;             pw.z = pk2(s[blk][8 * s2 + 4], s[blk][8 * s2 + 5]); pw.w = pk2(s[blk][8 * s2 + 6], s[blk][8 * s2 + 7]);
;             const bf16x8 pf = __builtin_bit_cast(bf16x8, pw);
; #pragma unroll
;             for (int db = 0; db < 4; ++db) o[db] = __builtin_amdgcn_mfma_f32_32x32x16_bf16(vf[st & 1][db], pf, o[db], 0, 0, 0);
;             __builtin_amdgcn_sched_barrier(0);
;         }
.Lfast_1353:
	s_nop 8
	v_max_f32_e32 v176, v97, v97
	v_max_f32_e32 v177, v96, v96
	v_max_f32_e32 v176, v177, v176
	v_max3_f32 v176, v176, v98, v99
	v_max3_f32 v176, v176, v100, v101
	v_max3_f32 v176, v176, v102, v103
	v_max3_f32 v176, v176, v104, v105
	v_max3_f32 v176, v176, v106, v107
	v_max3_f32 v176, v176, v108, v109
	v_max3_f32 v176, v176, v110, v111
	v_max3_f32 v176, v176, v80, v81
	v_max3_f32 v176, v176, v82, v83
	v_max3_f32 v176, v176, v84, v85
	v_max3_f32 v176, v176, v86, v87
	v_max3_f32 v176, v176, v88, v89
	v_max3_f32 v176, v176, v90, v91
	v_max3_f32 v176, v176, v92, v93
	v_max3_f32 v176, v176, v94, v95
	v_cmp_lt_f32_e32 vcc, 0x42000000, v176
	v_cmp_gt_f32_e64 s[98:99], s32, v176
	s_nop 1
	s_or_b64 vcc, vcc, s[98:99]
	s_cbranch_vccz .Lfast_1355
	v_add_u32_e32 v218, 0, v181
	v_add_u32_e32 v205, 0, v180
	v_cndmask_b32_e64 v176, 0, 1, s[8:9]
	v_cmp_ne_u32_e64 s[4:5], 1, v176
	s_cmp_eq_u32 s32, 0xc2000000
	s_cselect_b32 s98, 0xff800000, 0
	v_mov_b32_e32 v174, s98
	s_branch .LBB0_1353
.Lfast_1355:
	s_mul_hi_u32 s6, s16, 0xaaaaaaab
	s_lshr_b32 s6, s6, 1
	s_mul_i32 s6, s6, 0xd800
	v_subrev_u32_e32 v183, s6, v215
	ds_read_b128 v[176:179], v183 offset:4608
	ds_read_b128 v[220:223], v183 offset:9216
	ds_read_b128 v[224:227], v183 offset:13824
	ds_read_b128 v[228:231], v183
	ds_read_b128 v[232:235], v183 offset:32
	ds_read_b128 v[236:239], v183 offset:4640
	ds_read_b128 v[240:243], v183 offset:9248
	ds_read_b128 v[244:247], v183 offset:13856
	v_exp_f32_e32 v96, v96
	v_exp_f32_e32 v97, v97
	v_exp_f32_e32 v98, v98
	v_exp_f32_e32 v99, v99
	v_exp_f32_e32 v100, v100
	v_exp_f32_e32 v101, v101
	v_exp_f32_e32 v102, v102
	v_exp_f32_e32 v103, v103
	v_cvt_pk_bf16_f32 v248, v96, v97
	v_cvt_pk_bf16_f32 v249, v98, v99
	v_cvt_pk_bf16_f32 v250, v100, v101
	v_cvt_pk_bf16_f32 v251, v102, v103
	s_waitcnt lgkmcnt(4)
	s_nop 0
	v_mfma_f32_32x32x16_bf16 v[64:79], v[228:231], v[248:251], v[64:79]
	v_exp_f32_e32 v104, v104
	v_exp_f32_e32 v105, v105
	v_mfma_f32_32x32x16_bf16 v[48:63], v[176:179], v[248:251], v[48:63]
	v_exp_f32_e32 v106, v106
	v_exp_f32_e32 v107, v107
	v_mfma_f32_32x32x16_bf16 v[32:47], v[220:223], v[248:251], v[32:47]
	v_exp_f32_e32 v108, v108
	v_exp_f32_e32 v109, v109
	v_mfma_f32_32x32x16_bf16 v[16:31], v[224:227], v[248:251], v[16:31]
	v_exp_f32_e32 v110, v110
	v_exp_f32_e32 v111, v111
	ds_read_b128 v[176:179], v183 offset:64
	ds_read_b128 v[220:223], v183 offset:4672
	ds_read_b128 v[224:227], v183 offset:9280
	ds_read_b128 v[228:231], v183 offset:13888
	v_cvt_pk_bf16_f32 v248, v104, v105
	v_cvt_pk_bf16_f32 v249, v106, v107
	v_cvt_pk_bf16_f32 v250, v108, v109
	v_cvt_pk_bf16_f32 v251, v110, v111
	s_waitcnt lgkmcnt(4)
	s_nop 0
	v_mfma_f32_32x32x16_bf16 v[64:79], v[232:235], v[248:251], v[64:79]
	v_exp_f32_e32 v80, v80
	v_exp_f32_e32 v81, v81
	v_add_f32_e32 v96, v97, v96
	v_add_f32_e32 v98, v99, v98
	v_mfma_f32_32x32x16_bf16 v[48:63], v[236:239], v[248:251], v[48:63]
	v_exp_f32_e32 v82, v82
	v_exp_f32_e32 v83, v83
	v_add_f32_e32 v100, v101, v100
	v_add_f32_e32 v102, v103, v102
	v_mfma_f32_32x32x16_bf16 v[32:47], v[240:243], v[248:251], v[32:47]
	v_exp_f32_e32 v84, v84
	v_exp_f32_e32 v85, v85
	v_add_f32_e32 v96, v98, v96
	v_add_f32_e32 v100, v102, v100
	v_mfma_f32_32x32x16_bf16 v[16:31], v[244:247], v[248:251], v[16:31]
	v_exp_f32_e32 v86, v86
	v_exp_f32_e32 v87, v87
	v_add_f32_e32 v96, v100, v96
	ds_read_b128 v[232:235], v183 offset:96
	ds_read_b128 v[236:239], v183 offset:4704
	ds_read_b128 v[240:243], v183 offset:9312
	ds_read_b128 v[244:247], v183 offset:13920
	v_cvt_pk_bf16_f32 v248, v80, v81
	v_cvt_pk_bf16_f32 v249, v82, v83
	v_cvt_pk_bf16_f32 v250, v84, v85
	v_cvt_pk_bf16_f32 v251, v86, v87
	s_waitcnt lgkmcnt(4)
	s_nop 0
	v_mfma_f32_32x32x16_bf16 v[64:79], v[176:179], v[248:251], v[64:79]
	v_exp_f32_e32 v88, v88
	v_exp_f32_e32 v89, v89
	v_add_f32_e32 v104, v105, v104
	v_add_f32_e32 v106, v107, v106
	v_mfma_f32_32x32x16_bf16 v[48:63], v[220:223], v[248:251], v[48:63]
	v_exp_f32_e32 v90, v90
	v_exp_f32_e32 v91, v91
	v_add_f32_e32 v108, v109, v108
	v_add_f32_e32 v110, v111, v110
	v_mfma_f32_32x32x16_bf16 v[32:47], v[224:227], v[248:251], v[32:47]
	v_exp_f32_e32 v92, v92
	v_exp_f32_e32 v93, v93
	v_add_f32_e32 v104, v106, v104
	v_add_f32_e32 v108, v110, v108
	v_mfma_f32_32x32x16_bf16 v[16:31], v[228:231], v[248:251], v[16:31]
	v_exp_f32_e32 v94, v94
	v_exp_f32_e32 v95, v95
	v_add_f32_e32 v104, v108, v104
	v_cvt_pk_bf16_f32 v176, v88, v89
	v_cvt_pk_bf16_f32 v177, v90, v91
	v_cvt_pk_bf16_f32 v178, v92, v93
	v_cvt_pk_bf16_f32 v179, v94, v95
	s_waitcnt lgkmcnt(0)
	s_nop 0
	v_mfma_f32_32x32x16_bf16 v[64:79], v[232:235], v[176:179], v[64:79]
	v_add_f32_e32 v80, v81, v80
	v_add_f32_e32 v82, v83, v82
	v_add_f32_e32 v84, v85, v84
	v_add_f32_e32 v86, v87, v86
	v_add_f32_e32 v88, v89, v88
	v_add_f32_e32 v90, v91, v90
	v_mfma_f32_32x32x16_bf16 v[48:63], v[236:239], v[176:179], v[48:63]
	v_add_f32_e32 v92, v93, v92
	v_add_f32_e32 v94, v95, v94
	v_add_f32_e32 v80, v82, v80
	v_add_f32_e32 v84, v86, v84
	v_add_f32_e32 v88, v90, v88
	v_add_f32_e32 v92, v94, v92
	v_mfma_f32_32x32x16_bf16 v[32:47], v[240:243], v[176:179], v[32:47]
	v_add_f32_e32 v80, v84, v80
	v_add_f32_e32 v88, v92, v88
	v_add_f32_e32 v96, v104, v96
	v_mfma_f32_32x32x16_bf16 v[16:31], v[244:247], v[176:179], v[16:31]
	v_add_f32_e32 v80, v88, v80
	v_add_f32_e32 v96, v80, v96
	s_andn2_b64 vcc, exec, s[10:11]
	s_cbranch_vccnz .Lfast_1361
	s_cmp_eq_u32 s12, 1
	s_cselect_b32 s12, 0, 0x6400
	s_add_i32 s12, s12, 0
	v_add_u32_e32 v176, s12, v209
	s_waitcnt vmcnt(0)
	ds_write_b128 v176, v[164:167]
	ds_write_b128 v181, v[160:163]
	v_add_u32_e32 v160, s12, v210
	ds_write_b128 v160, v[156:159]
	ds_write_b128 v180, v[152:155]
	v_add_u32_e32 v152, s12, v211
	s_cmp_ge_u32 s18, s3
	s_mov_b64 s[12:13], -1
	ds_write_b128 v152, v[148:151]
	s_cbranch_scc0 .Lfast_1358
	s_add_i32 s12, s15, s19
	s_add_i32 s21, s12, 0xfffff000
	s_mov_b64 s[12:13], 0

; DI float shx(float v, int m, int lane) { return __builtin_bit_cast(float, __builtin_amdgcn_ds_bpermute((lane ^ m) << 2, __builtin_bit_cast(int, v))); }
; template <int DQ>
; DI void attn_item(const Frame& F, const AttnItem& it, const LAS float* rpb_lds) {
;     ...
;     for (int ti = 0; ti < ntile; ++ti) {
;         qk(ti);
;         if (grpB) { if (ti + 1 < ntile) lstore(ti + 1); if (ti + 2 < ntile) gload(ti + 2); __syncthreads(); }
;         smpv(ti);
;         if (!grpB) { if (ti + 1 < ntile) lstore(ti + 1); if (ti + 2 < ntile) gload(ti + 2); __syncthreads(); }
;     }
;     const float lt = lrun + shx(lrun, 32, lane), inv = 1.f / lt;
.Lfast_1361:
	s_add_i32 s18, s18, 1
	s_add_i32 s19, s19, 64
	s_add_i32 s17, s17, 1
	s_add_i32 s12, s20, s18
	s_add_i32 s16, s16, 1
	v_add_f32_e32 v216, v216, v96
	v_add_u32_e32 v213, 0x4800, v213
	v_add_u32_e32 v214, 0x4800, v214
	s_cmp_lg_u32 s12, 4
	v_add_u32_e32 v215, 0x4800, v215
	s_cbranch_scc0 .Lfast_exit
	s_mov_b32 s32, 0xff800000
	s_branch .Lfast_1347
.Lfast_exit:
	v_mov_b32_e32 v205, v216
	v_mov_b32_e32 v217, 0
	v_cndmask_b32_e64 v176, 0, 1, s[8:9]
	v_cmp_ne_u32_e64 s[4:5], 1, v176
	v_cndmask_b32_e64 v177, 0, 1, s[10:11]
	v_cmp_ne_u32_e64 s[6:7], 1, v177
	s_branch .LBB0_1363
